# peeled first iteration: waits of segments 3 and 4 moved behind their MFMAs (stores overlap three segments)
# speedup vs baseline: 1.0024x; 1.0024x over previous
.Lrwp1_bdone:
	s_mov_b32 s98, 0
	s_waitcnt lgkmcnt(0)
	s_barrier
	s_setprio 1
	s_waitcnt lgkmcnt(0)
	v_mfma_f32_16x16x32_bf16 v[62:65], v[148:151], v[188:191], 0
	v_mfma_f32_16x16x32_bf16 v[58:61], v[164:167], v[188:191], 0
	v_mfma_f32_16x16x32_bf16 v[46:49], v[148:151], v[196:199], 0
	v_mfma_f32_16x16x32_bf16 v[42:45], v[164:167], v[196:199], 0
	v_mfma_f32_16x16x32_bf16 v[30:33], v[148:151], v[204:207], 0
	v_mfma_f32_16x16x32_bf16 v[26:29], v[164:167], v[204:207], 0
	v_mfma_f32_16x16x32_bf16 v[14:17], v[148:151], v[212:215], 0
	v_mfma_f32_16x16x32_bf16 v[10:13], v[164:167], v[212:215], 0
	v_mfma_f32_16x16x32_bf16 v[62:65], v[152:155], v[192:195], v[62:65]
	v_mfma_f32_16x16x32_bf16 v[58:61], v[168:171], v[192:195], v[58:61]
	v_mfma_f32_16x16x32_bf16 v[46:49], v[152:155], v[200:203], v[46:49]
	v_mfma_f32_16x16x32_bf16 v[42:45], v[168:171], v[200:203], v[42:45]
	v_mfma_f32_16x16x32_bf16 v[30:33], v[152:155], v[208:211], v[30:33]
	v_mfma_f32_16x16x32_bf16 v[26:29], v[168:171], v[208:211], v[26:29]
	v_mfma_f32_16x16x32_bf16 v[14:17], v[152:155], v[216:219], v[14:17]
	v_mfma_f32_16x16x32_bf16 v[10:13], v[168:171], v[216:219], v[10:13]
	s_setprio 0
	s_setprio 1
	v_mfma_f32_16x16x32_bf16 v[54:57], v[172:175], v[188:191], 0
	v_mfma_f32_16x16x32_bf16 v[50:53], v[180:183], v[188:191], 0
	v_mfma_f32_16x16x32_bf16 v[38:41], v[172:175], v[196:199], 0
	v_mfma_f32_16x16x32_bf16 v[34:37], v[180:183], v[196:199], 0
	v_mfma_f32_16x16x32_bf16 v[22:25], v[172:175], v[204:207], 0
	v_mfma_f32_16x16x32_bf16 v[18:21], v[180:183], v[204:207], 0
	v_mfma_f32_16x16x32_bf16 v[6:9], v[172:175], v[212:215], 0
	v_mfma_f32_16x16x32_bf16 v[2:5], v[180:183], v[212:215], 0
	v_mfma_f32_16x16x32_bf16 v[54:57], v[176:179], v[192:195], v[54:57]
	v_mfma_f32_16x16x32_bf16 v[50:53], v[184:187], v[192:195], v[50:53]
	v_mfma_f32_16x16x32_bf16 v[38:41], v[176:179], v[200:203], v[38:41]
	v_mfma_f32_16x16x32_bf16 v[34:37], v[184:187], v[200:203], v[34:37]
	v_mfma_f32_16x16x32_bf16 v[22:25], v[176:179], v[208:211], v[22:25]
	v_mfma_f32_16x16x32_bf16 v[18:21], v[184:187], v[208:211], v[18:21]
	v_mfma_f32_16x16x32_bf16 v[6:9], v[176:179], v[216:219], v[6:9]
	v_mfma_f32_16x16x32_bf16 v[2:5], v[184:187], v[216:219], v[2:5]
	s_setprio 0
	s_barrier
	s_add_i32 s88, 0, 0x18000
	v_add_u32_e32 v138, s88, v158
	s_add_i32 s89, 0, 0x1c000
	ds_read_b128 v[148:151], v138
	ds_read_b128 v[152:155], v138 offset:1024
	ds_read_b128 v[164:167], v138 offset:2048
	ds_read_b128 v[168:171], v138 offset:3072
	v_add_u32_e32 v138, s89, v158
	ds_read_b128 v[172:175], v138
	ds_read_b128 v[176:179], v138 offset:1024
	ds_read_b128 v[180:183], v138 offset:2048
	ds_read_b128 v[184:187], v138 offset:3072
	s_add_u32 s6, s66, 0x40000
	s_addc_u32 s7, s67, 0
	s_mov_b32 m0, s74
	v_lshl_add_u64 v[228:229], s[6:7], 0, v[130:131]
	ds_read_b128 v[188:191], v161 offset:32768
	ds_read_b128 v[192:195], v161 offset:33792
	ds_read_b128 v[196:199], v161 offset:34816
	ds_read_b128 v[200:203], v161 offset:35840
	ds_read_b128 v[204:207], v161 offset:36864
	ds_read_b128 v[208:211], v161 offset:37888
	ds_read_b128 v[212:215], v161 offset:38912
	ds_read_b128 v[216:219], v161 offset:39936
	global_load_lds_dwordx4 v[228:229], off
	v_lshl_add_u64 v[228:229], s[6:7], 0, v[134:135]
	s_mov_b32 m0, s75
	s_nop 0
	global_load_lds_dwordx4 v[228:229], off
	s_waitcnt lgkmcnt(0)
	s_barrier
	s_setprio 1
	s_waitcnt lgkmcnt(0)
	v_mfma_f32_16x16x32_bf16 v[126:129], v[148:151], v[188:191], v[126:129]
	v_mfma_f32_16x16x32_bf16 v[122:125], v[164:167], v[188:191], v[122:125]
	v_mfma_f32_16x16x32_bf16 v[110:113], v[148:151], v[196:199], v[110:113]
	v_mfma_f32_16x16x32_bf16 v[106:109], v[164:167], v[196:199], v[106:109]
	v_mfma_f32_16x16x32_bf16 v[94:97], v[148:151], v[204:207], v[94:97]
	v_mfma_f32_16x16x32_bf16 v[90:93], v[164:167], v[204:207], v[90:93]
	v_mfma_f32_16x16x32_bf16 v[78:81], v[148:151], v[212:215], v[78:81]
	v_mfma_f32_16x16x32_bf16 v[74:77], v[164:167], v[212:215], v[74:77]
	v_mfma_f32_16x16x32_bf16 v[126:129], v[152:155], v[192:195], v[126:129]
	v_mfma_f32_16x16x32_bf16 v[122:125], v[168:171], v[192:195], v[122:125]
	v_mfma_f32_16x16x32_bf16 v[110:113], v[152:155], v[200:203], v[110:113]
	v_mfma_f32_16x16x32_bf16 v[106:109], v[168:171], v[200:203], v[106:109]
	v_mfma_f32_16x16x32_bf16 v[94:97], v[152:155], v[208:211], v[94:97]
	v_mfma_f32_16x16x32_bf16 v[90:93], v[168:171], v[208:211], v[90:93]
	v_mfma_f32_16x16x32_bf16 v[78:81], v[152:155], v[216:219], v[78:81]
	v_mfma_f32_16x16x32_bf16 v[74:77], v[168:171], v[216:219], v[74:77]
	s_setprio 0
	s_setprio 1
	v_mfma_f32_16x16x32_bf16 v[118:121], v[172:175], v[188:191], v[118:121]
	v_mfma_f32_16x16x32_bf16 v[114:117], v[180:183], v[188:191], v[114:117]
	v_mfma_f32_16x16x32_bf16 v[102:105], v[172:175], v[196:199], v[102:105]
	v_mfma_f32_16x16x32_bf16 v[98:101], v[180:183], v[196:199], v[98:101]
	v_mfma_f32_16x16x32_bf16 v[86:89], v[172:175], v[204:207], v[86:89]
	v_mfma_f32_16x16x32_bf16 v[82:85], v[180:183], v[204:207], v[82:85]
	v_mfma_f32_16x16x32_bf16 v[70:73], v[172:175], v[212:215], v[70:73]
	v_mfma_f32_16x16x32_bf16 v[66:69], v[180:183], v[212:215], v[66:69]
	v_mfma_f32_16x16x32_bf16 v[118:121], v[176:179], v[192:195], v[118:121]
	v_mfma_f32_16x16x32_bf16 v[114:117], v[184:187], v[192:195], v[114:117]
	v_mfma_f32_16x16x32_bf16 v[102:105], v[176:179], v[200:203], v[102:105]
	v_mfma_f32_16x16x32_bf16 v[98:101], v[184:187], v[200:203], v[98:101]
	v_mfma_f32_16x16x32_bf16 v[86:89], v[176:179], v[208:211], v[86:89]
	v_mfma_f32_16x16x32_bf16 v[82:85], v[184:187], v[208:211], v[82:85]
	v_mfma_f32_16x16x32_bf16 v[70:73], v[176:179], v[216:219], v[70:73]
	v_mfma_f32_16x16x32_bf16 v[66:69], v[184:187], v[216:219], v[66:69]
	s_setprio 0
	s_waitcnt vmcnt(8)
	s_barrier
	s_add_i32 s6, s88, s47
	v_lshl_add_u64 v[220:221], v[220:221], 0, s[20:21]
	s_mov_b32 m0, s6
	ds_read_b128 v[188:191], v161 offset:49152
	ds_read_b128 v[192:195], v161 offset:50176
	ds_read_b128 v[196:199], v161 offset:51200
	ds_read_b128 v[200:203], v161 offset:52224
	ds_read_b128 v[204:207], v161 offset:53248
	ds_read_b128 v[208:211], v161 offset:54272
	ds_read_b128 v[212:215], v161 offset:55296
	ds_read_b128 v[216:219], v161 offset:56320
	global_load_lds_dwordx4 v[220:221], off
	s_add_i32 m0, s6, 0x2000
	s_add_u32 s6, s64, 0x40080
	v_lshl_add_u64 v[220:221], v[222:223], 0, s[20:21]
	s_addc_u32 s7, s65, 0
	s_add_i32 s64, s89, s47
	global_load_lds_dwordx4 v[220:221], off
	v_lshl_add_u64 v[220:221], s[6:7], 0, v[132:133]
	s_mov_b32 m0, s64
	s_nop 0
	global_load_lds_dwordx4 v[220:221], off
	v_lshl_add_u64 v[220:221], s[6:7], 0, v[136:137]
	s_add_i32 m0, s64, 0x2000
	s_nop 0
	global_load_lds_dwordx4 v[220:221], off
	v_lshl_add_u64 v[220:221], v[224:225], 0, s[20:21]
	s_mov_b32 m0, s77
	s_nop 0
	global_load_lds_dwordx4 v[220:221], off
	v_lshl_add_u64 v[220:221], v[226:227], 0, s[20:21]
	s_mov_b32 m0, s78
	s_nop 0
	global_load_lds_dwordx4 v[220:221], off
	s_waitcnt lgkmcnt(0)
	s_barrier
	s_setprio 1
	s_waitcnt lgkmcnt(0)
	v_mfma_f32_16x16x32_bf16 v[62:65], v[148:151], v[188:191], v[62:65]
	v_mfma_f32_16x16x32_bf16 v[58:61], v[164:167], v[188:191], v[58:61]
	v_mfma_f32_16x16x32_bf16 v[46:49], v[148:151], v[196:199], v[46:49]
	v_mfma_f32_16x16x32_bf16 v[42:45], v[164:167], v[196:199], v[42:45]
	v_mfma_f32_16x16x32_bf16 v[30:33], v[148:151], v[204:207], v[30:33]
	v_mfma_f32_16x16x32_bf16 v[26:29], v[164:167], v[204:207], v[26:29]
	v_mfma_f32_16x16x32_bf16 v[14:17], v[148:151], v[212:215], v[14:17]
	v_mfma_f32_16x16x32_bf16 v[10:13], v[164:167], v[212:215], v[10:13]
	v_mfma_f32_16x16x32_bf16 v[62:65], v[152:155], v[192:195], v[62:65]
	v_mfma_f32_16x16x32_bf16 v[58:61], v[168:171], v[192:195], v[58:61]
	v_mfma_f32_16x16x32_bf16 v[46:49], v[152:155], v[200:203], v[46:49]
	v_mfma_f32_16x16x32_bf16 v[42:45], v[168:171], v[200:203], v[42:45]
	v_mfma_f32_16x16x32_bf16 v[30:33], v[152:155], v[208:211], v[30:33]
	v_mfma_f32_16x16x32_bf16 v[26:29], v[168:171], v[208:211], v[26:29]
	v_mfma_f32_16x16x32_bf16 v[14:17], v[152:155], v[216:219], v[14:17]
	v_mfma_f32_16x16x32_bf16 v[10:13], v[168:171], v[216:219], v[10:13]
	s_setprio 0
	s_setprio 1
	v_mfma_f32_16x16x32_bf16 v[54:57], v[172:175], v[188:191], v[54:57]
	v_mfma_f32_16x16x32_bf16 v[50:53], v[180:183], v[188:191], v[50:53]
	v_mfma_f32_16x16x32_bf16 v[38:41], v[172:175], v[196:199], v[38:41]
	v_mfma_f32_16x16x32_bf16 v[34:37], v[180:183], v[196:199], v[34:37]
	v_mfma_f32_16x16x32_bf16 v[22:25], v[172:175], v[204:207], v[22:25]
	v_mfma_f32_16x16x32_bf16 v[18:21], v[180:183], v[204:207], v[18:21]
	v_mfma_f32_16x16x32_bf16 v[6:9], v[172:175], v[212:215], v[6:9]
	v_mfma_f32_16x16x32_bf16 v[2:5], v[180:183], v[212:215], v[2:5]
	v_mfma_f32_16x16x32_bf16 v[54:57], v[176:179], v[192:195], v[54:57]
	v_mfma_f32_16x16x32_bf16 v[50:53], v[184:187], v[192:195], v[50:53]
	v_mfma_f32_16x16x32_bf16 v[38:41], v[176:179], v[200:203], v[38:41]
	v_mfma_f32_16x16x32_bf16 v[34:37], v[184:187], v[200:203], v[34:37]
	v_mfma_f32_16x16x32_bf16 v[22:25], v[176:179], v[208:211], v[22:25]
	v_mfma_f32_16x16x32_bf16 v[18:21], v[184:187], v[208:211], v[18:21]
	v_mfma_f32_16x16x32_bf16 v[6:9], v[176:179], v[216:219], v[6:9]
	v_mfma_f32_16x16x32_bf16 v[2:5], v[184:187], v[216:219], v[2:5]
	s_setprio 0
	s_waitcnt vmcnt(8)
	s_barrier
	s_add_i32 s63, s63, 2
	s_add_u32 s60, s60, 0x100
	s_addc_u32 s61, s61, 0
	s_add_u32 s49, s49, 0x100
	s_addc_u32 s55, s55, 0
	s_cmp_gt_u32 s63, 13
	s_cbranch_scc0 .LBB0_175
	s_branch .Lrwp1_exit

.Lrwp3a_bdone:
	s_mov_b32 s100, 0
	s_waitcnt lgkmcnt(0)
	s_barrier
	s_setprio 1
	s_waitcnt lgkmcnt(0)
	v_mfma_f32_16x16x32_bf16 v[62:65], v[154:157], v[186:189], 0
	v_mfma_f32_16x16x32_bf16 v[58:61], v[162:165], v[186:189], 0
	v_mfma_f32_16x16x32_bf16 v[50:53], v[154:157], v[194:197], 0
	v_mfma_f32_16x16x32_bf16 v[42:45], v[162:165], v[194:197], 0
	v_mfma_f32_16x16x32_bf16 v[34:37], v[154:157], v[202:205], 0
	v_mfma_f32_16x16x32_bf16 v[26:29], v[162:165], v[202:205], 0
	v_mfma_f32_16x16x32_bf16 v[18:21], v[154:157], v[210:213], 0
	v_mfma_f32_16x16x32_bf16 v[10:13], v[162:165], v[210:213], 0
	v_mfma_f32_16x16x32_bf16 v[62:65], v[158:161], v[190:193], v[62:65]
	v_mfma_f32_16x16x32_bf16 v[58:61], v[166:169], v[190:193], v[58:61]
	v_mfma_f32_16x16x32_bf16 v[50:53], v[158:161], v[198:201], v[50:53]
	v_mfma_f32_16x16x32_bf16 v[42:45], v[166:169], v[198:201], v[42:45]
	v_mfma_f32_16x16x32_bf16 v[34:37], v[158:161], v[206:209], v[34:37]
	v_mfma_f32_16x16x32_bf16 v[26:29], v[166:169], v[206:209], v[26:29]
	v_mfma_f32_16x16x32_bf16 v[18:21], v[158:161], v[214:217], v[18:21]
	v_mfma_f32_16x16x32_bf16 v[10:13], v[166:169], v[214:217], v[10:13]
	s_setprio 0
	s_setprio 1
	v_mfma_f32_16x16x32_bf16 v[54:57], v[170:173], v[186:189], 0
	v_mfma_f32_16x16x32_bf16 v[46:49], v[178:181], v[186:189], 0
	v_mfma_f32_16x16x32_bf16 v[38:41], v[170:173], v[194:197], 0
	v_mfma_f32_16x16x32_bf16 v[30:33], v[178:181], v[194:197], 0
	v_mfma_f32_16x16x32_bf16 v[22:25], v[170:173], v[202:205], 0
	v_mfma_f32_16x16x32_bf16 v[14:17], v[178:181], v[202:205], 0
	v_mfma_f32_16x16x32_bf16 v[6:9], v[170:173], v[210:213], 0
	v_mfma_f32_16x16x32_bf16 v[2:5], v[178:181], v[210:213], 0
	v_mfma_f32_16x16x32_bf16 v[54:57], v[174:177], v[190:193], v[54:57]
	v_mfma_f32_16x16x32_bf16 v[46:49], v[182:185], v[190:193], v[46:49]
	v_mfma_f32_16x16x32_bf16 v[38:41], v[174:177], v[198:201], v[38:41]
	v_mfma_f32_16x16x32_bf16 v[30:33], v[182:185], v[198:201], v[30:33]
	v_mfma_f32_16x16x32_bf16 v[22:25], v[174:177], v[206:209], v[22:25]
	v_mfma_f32_16x16x32_bf16 v[14:17], v[182:185], v[206:209], v[14:17]
	v_mfma_f32_16x16x32_bf16 v[6:9], v[174:177], v[214:217], v[6:9]
	v_mfma_f32_16x16x32_bf16 v[2:5], v[182:185], v[214:217], v[2:5]
	s_setprio 0
	s_barrier
	s_add_i32 s97, 0, 0x18000
	v_add_u32_e32 v153, s97, v149
	s_add_i32 vcc_lo, 0, 0x1c000
	ds_read_b128 v[154:157], v153
	ds_read_b128 v[158:161], v153 offset:1024
	ds_read_b128 v[162:165], v153 offset:2048
	ds_read_b128 v[166:169], v153 offset:3072
	v_add_u32_e32 v153, vcc_lo, v149
	ds_read_b128 v[170:173], v153
	ds_read_b128 v[174:177], v153 offset:1024
	ds_read_b128 v[178:181], v153 offset:2048
	ds_read_b128 v[182:185], v153 offset:3072
	s_add_u32 s6, s72, 0x20000
	s_addc_u32 s7, s73, 0
	s_mov_b32 m0, s77
	v_lshl_add_u64 v[224:225], s[6:7], 0, v[130:131]
	ds_read_b128 v[186:189], v152 offset:32768
	ds_read_b128 v[190:193], v152 offset:33792
	ds_read_b128 v[194:197], v152 offset:34816
	ds_read_b128 v[198:201], v152 offset:35840
	ds_read_b128 v[202:205], v152 offset:36864
	ds_read_b128 v[206:209], v152 offset:37888
	ds_read_b128 v[210:213], v152 offset:38912
	ds_read_b128 v[214:217], v152 offset:39936
	global_load_lds_dwordx4 v[224:225], off
	v_lshl_add_u64 v[224:225], s[6:7], 0, v[134:135]
	s_mov_b32 m0, s78
	s_nop 0
	global_load_lds_dwordx4 v[224:225], off
	s_waitcnt lgkmcnt(0)
	s_barrier
	s_setprio 1
	s_waitcnt lgkmcnt(0)
	v_mfma_f32_16x16x32_bf16 v[126:129], v[154:157], v[186:189], v[126:129]
	v_mfma_f32_16x16x32_bf16 v[122:125], v[162:165], v[186:189], v[122:125]
	v_mfma_f32_16x16x32_bf16 v[114:117], v[154:157], v[194:197], v[114:117]
	v_mfma_f32_16x16x32_bf16 v[106:109], v[162:165], v[194:197], v[106:109]
	v_mfma_f32_16x16x32_bf16 v[98:101], v[154:157], v[202:205], v[98:101]
	v_mfma_f32_16x16x32_bf16 v[90:93], v[162:165], v[202:205], v[90:93]
	v_mfma_f32_16x16x32_bf16 v[82:85], v[154:157], v[210:213], v[82:85]
	v_mfma_f32_16x16x32_bf16 v[74:77], v[162:165], v[210:213], v[74:77]
	v_mfma_f32_16x16x32_bf16 v[126:129], v[158:161], v[190:193], v[126:129]
	v_mfma_f32_16x16x32_bf16 v[122:125], v[166:169], v[190:193], v[122:125]
	v_mfma_f32_16x16x32_bf16 v[114:117], v[158:161], v[198:201], v[114:117]
	v_mfma_f32_16x16x32_bf16 v[106:109], v[166:169], v[198:201], v[106:109]
	v_mfma_f32_16x16x32_bf16 v[98:101], v[158:161], v[206:209], v[98:101]
	v_mfma_f32_16x16x32_bf16 v[90:93], v[166:169], v[206:209], v[90:93]
	v_mfma_f32_16x16x32_bf16 v[82:85], v[158:161], v[214:217], v[82:85]
	v_mfma_f32_16x16x32_bf16 v[74:77], v[166:169], v[214:217], v[74:77]
	s_setprio 0
	s_setprio 1
	v_mfma_f32_16x16x32_bf16 v[118:121], v[170:173], v[186:189], v[118:121]
	v_mfma_f32_16x16x32_bf16 v[110:113], v[178:181], v[186:189], v[110:113]
	v_mfma_f32_16x16x32_bf16 v[102:105], v[170:173], v[194:197], v[102:105]
	v_mfma_f32_16x16x32_bf16 v[94:97], v[178:181], v[194:197], v[94:97]
	v_mfma_f32_16x16x32_bf16 v[86:89], v[170:173], v[202:205], v[86:89]
	v_mfma_f32_16x16x32_bf16 v[78:81], v[178:181], v[202:205], v[78:81]
	v_mfma_f32_16x16x32_bf16 v[70:73], v[170:173], v[210:213], v[70:73]
	v_mfma_f32_16x16x32_bf16 v[66:69], v[178:181], v[210:213], v[66:69]
	v_mfma_f32_16x16x32_bf16 v[118:121], v[174:177], v[190:193], v[118:121]
	v_mfma_f32_16x16x32_bf16 v[110:113], v[182:185], v[190:193], v[110:113]
	v_mfma_f32_16x16x32_bf16 v[102:105], v[174:177], v[198:201], v[102:105]
	v_mfma_f32_16x16x32_bf16 v[94:97], v[182:185], v[198:201], v[94:97]
	v_mfma_f32_16x16x32_bf16 v[86:89], v[174:177], v[206:209], v[86:89]
	v_mfma_f32_16x16x32_bf16 v[78:81], v[182:185], v[206:209], v[78:81]
	v_mfma_f32_16x16x32_bf16 v[70:73], v[174:177], v[214:217], v[70:73]
	v_mfma_f32_16x16x32_bf16 v[66:69], v[182:185], v[214:217], v[66:69]
	s_setprio 0
	s_waitcnt vmcnt(8)
	s_barrier
	s_add_i32 s6, s97, s31
	v_lshl_add_u64 v[146:147], v[146:147], 0, s[12:13]
	s_mov_b32 m0, s6
	ds_read_b128 v[186:189], v152 offset:49152
	ds_read_b128 v[190:193], v152 offset:50176
	ds_read_b128 v[194:197], v152 offset:51200
	ds_read_b128 v[198:201], v152 offset:52224
	ds_read_b128 v[202:205], v152 offset:53248
	ds_read_b128 v[206:209], v152 offset:54272
	ds_read_b128 v[210:213], v152 offset:55296
	ds_read_b128 v[214:217], v152 offset:56320
	global_load_lds_dwordx4 v[146:147], off
	s_add_i32 m0, s6, 0x2000
	s_add_u32 s6, s70, 0x20080
	v_lshl_add_u64 v[146:147], v[218:219], 0, s[12:13]
	s_addc_u32 s7, s71, 0
	s_add_i32 s70, vcc_lo, s31
	global_load_lds_dwordx4 v[146:147], off
	v_lshl_add_u64 v[146:147], s[6:7], 0, v[132:133]
	s_mov_b32 m0, s70
	s_nop 0
	global_load_lds_dwordx4 v[146:147], off
	v_lshl_add_u64 v[146:147], s[6:7], 0, v[136:137]
	s_add_i32 m0, s70, 0x2000
	s_nop 0
	global_load_lds_dwordx4 v[146:147], off
	v_lshl_add_u64 v[146:147], v[220:221], 0, s[12:13]
	s_mov_b32 m0, s82
	s_nop 0
	global_load_lds_dwordx4 v[146:147], off
	v_lshl_add_u64 v[146:147], v[222:223], 0, s[12:13]
	s_mov_b32 m0, s83
	s_nop 0
	global_load_lds_dwordx4 v[146:147], off
	s_waitcnt lgkmcnt(0)
	s_barrier
	s_setprio 1
	s_waitcnt lgkmcnt(0)
	v_mfma_f32_16x16x32_bf16 v[62:65], v[154:157], v[186:189], v[62:65]
	v_mfma_f32_16x16x32_bf16 v[58:61], v[162:165], v[186:189], v[58:61]
	v_mfma_f32_16x16x32_bf16 v[50:53], v[154:157], v[194:197], v[50:53]
	v_mfma_f32_16x16x32_bf16 v[42:45], v[162:165], v[194:197], v[42:45]
	v_mfma_f32_16x16x32_bf16 v[34:37], v[154:157], v[202:205], v[34:37]
	v_mfma_f32_16x16x32_bf16 v[26:29], v[162:165], v[202:205], v[26:29]
	v_mfma_f32_16x16x32_bf16 v[18:21], v[154:157], v[210:213], v[18:21]
	v_mfma_f32_16x16x32_bf16 v[10:13], v[162:165], v[210:213], v[10:13]
	v_mfma_f32_16x16x32_bf16 v[62:65], v[158:161], v[190:193], v[62:65]
	v_mfma_f32_16x16x32_bf16 v[58:61], v[166:169], v[190:193], v[58:61]
	v_mfma_f32_16x16x32_bf16 v[50:53], v[158:161], v[198:201], v[50:53]
	v_mfma_f32_16x16x32_bf16 v[42:45], v[166:169], v[198:201], v[42:45]
	v_mfma_f32_16x16x32_bf16 v[34:37], v[158:161], v[206:209], v[34:37]
	v_mfma_f32_16x16x32_bf16 v[26:29], v[166:169], v[206:209], v[26:29]
	v_mfma_f32_16x16x32_bf16 v[18:21], v[158:161], v[214:217], v[18:21]
	v_mfma_f32_16x16x32_bf16 v[10:13], v[166:169], v[214:217], v[10:13]
	s_setprio 0
	s_setprio 1
	v_mfma_f32_16x16x32_bf16 v[54:57], v[170:173], v[186:189], v[54:57]
	v_mfma_f32_16x16x32_bf16 v[46:49], v[178:181], v[186:189], v[46:49]
	v_mfma_f32_16x16x32_bf16 v[38:41], v[170:173], v[194:197], v[38:41]
	v_mfma_f32_16x16x32_bf16 v[30:33], v[178:181], v[194:197], v[30:33]
	v_mfma_f32_16x16x32_bf16 v[22:25], v[170:173], v[202:205], v[22:25]
	v_mfma_f32_16x16x32_bf16 v[14:17], v[178:181], v[202:205], v[14:17]
	v_mfma_f32_16x16x32_bf16 v[6:9], v[170:173], v[210:213], v[6:9]
	v_mfma_f32_16x16x32_bf16 v[2:5], v[178:181], v[210:213], v[2:5]
	v_mfma_f32_16x16x32_bf16 v[54:57], v[174:177], v[190:193], v[54:57]
	v_mfma_f32_16x16x32_bf16 v[46:49], v[182:185], v[190:193], v[46:49]
	v_mfma_f32_16x16x32_bf16 v[38:41], v[174:177], v[198:201], v[38:41]
	v_mfma_f32_16x16x32_bf16 v[30:33], v[182:185], v[198:201], v[30:33]
	v_mfma_f32_16x16x32_bf16 v[22:25], v[174:177], v[206:209], v[22:25]
	v_mfma_f32_16x16x32_bf16 v[14:17], v[182:185], v[206:209], v[14:17]
	v_mfma_f32_16x16x32_bf16 v[6:9], v[174:177], v[214:217], v[6:9]
	v_mfma_f32_16x16x32_bf16 v[2:5], v[182:185], v[214:217], v[2:5]
	s_setprio 0
	s_waitcnt vmcnt(8)
	s_barrier
	s_add_i32 s96, s96, 2
	s_add_u32 s66, s66, 0x100
	s_addc_u32 s67, s67, 0
	s_add_u32 s94, s94, 0x100
	s_addc_u32 s95, s95, 0
	s_cmp_gt_u32 s96, 5
	s_cbranch_scc0 .LBB0_560
	s_branch .Lrwp3a_exit

.Lrwp3b_bdone:
	s_mov_b32 s100, 0
	s_waitcnt lgkmcnt(0)
	s_barrier
	s_setprio 1
	s_waitcnt lgkmcnt(0)
	v_mfma_f32_16x16x32_bf16 v[62:65], v[154:157], v[186:189], 0
	v_mfma_f32_16x16x32_bf16 v[58:61], v[162:165], v[186:189], 0
	v_mfma_f32_16x16x32_bf16 v[46:49], v[154:157], v[194:197], 0
	v_mfma_f32_16x16x32_bf16 v[42:45], v[162:165], v[194:197], 0
	v_mfma_f32_16x16x32_bf16 v[30:33], v[154:157], v[202:205], 0
	v_mfma_f32_16x16x32_bf16 v[26:29], v[162:165], v[202:205], 0
	v_mfma_f32_16x16x32_bf16 v[14:17], v[154:157], v[210:213], 0
	v_mfma_f32_16x16x32_bf16 v[10:13], v[162:165], v[210:213], 0
	v_mfma_f32_16x16x32_bf16 v[62:65], v[158:161], v[190:193], v[62:65]
	v_mfma_f32_16x16x32_bf16 v[58:61], v[166:169], v[190:193], v[58:61]
	v_mfma_f32_16x16x32_bf16 v[46:49], v[158:161], v[198:201], v[46:49]
	v_mfma_f32_16x16x32_bf16 v[42:45], v[166:169], v[198:201], v[42:45]
	v_mfma_f32_16x16x32_bf16 v[30:33], v[158:161], v[206:209], v[30:33]
	v_mfma_f32_16x16x32_bf16 v[26:29], v[166:169], v[206:209], v[26:29]
	v_mfma_f32_16x16x32_bf16 v[14:17], v[158:161], v[214:217], v[14:17]
	v_mfma_f32_16x16x32_bf16 v[10:13], v[166:169], v[214:217], v[10:13]
	s_setprio 0
	s_setprio 1
	v_mfma_f32_16x16x32_bf16 v[54:57], v[170:173], v[186:189], 0
	v_mfma_f32_16x16x32_bf16 v[50:53], v[178:181], v[186:189], 0
	v_mfma_f32_16x16x32_bf16 v[38:41], v[170:173], v[194:197], 0
	v_mfma_f32_16x16x32_bf16 v[34:37], v[178:181], v[194:197], 0
	v_mfma_f32_16x16x32_bf16 v[22:25], v[170:173], v[202:205], 0
	v_mfma_f32_16x16x32_bf16 v[18:21], v[178:181], v[202:205], 0
	v_mfma_f32_16x16x32_bf16 v[6:9], v[170:173], v[210:213], 0
	v_mfma_f32_16x16x32_bf16 v[2:5], v[178:181], v[210:213], 0
	v_mfma_f32_16x16x32_bf16 v[54:57], v[174:177], v[190:193], v[54:57]
	v_mfma_f32_16x16x32_bf16 v[50:53], v[182:185], v[190:193], v[50:53]
	v_mfma_f32_16x16x32_bf16 v[38:41], v[174:177], v[198:201], v[38:41]
	v_mfma_f32_16x16x32_bf16 v[34:37], v[182:185], v[198:201], v[34:37]
	v_mfma_f32_16x16x32_bf16 v[22:25], v[174:177], v[206:209], v[22:25]
	v_mfma_f32_16x16x32_bf16 v[18:21], v[182:185], v[206:209], v[18:21]
	v_mfma_f32_16x16x32_bf16 v[6:9], v[174:177], v[214:217], v[6:9]
	v_mfma_f32_16x16x32_bf16 v[2:5], v[182:185], v[214:217], v[2:5]
	s_setprio 0
	s_barrier
	s_add_i32 s95, 0, 0x18000
	v_add_u32_e32 v153, s95, v149
	s_add_i32 s96, 0, 0x1c000
	ds_read_b128 v[154:157], v153
	ds_read_b128 v[158:161], v153 offset:1024
	ds_read_b128 v[162:165], v153 offset:2048
	ds_read_b128 v[166:169], v153 offset:3072
	v_add_u32_e32 v153, s96, v149
	ds_read_b128 v[170:173], v153
	ds_read_b128 v[174:177], v153 offset:1024
	ds_read_b128 v[178:181], v153 offset:2048
	ds_read_b128 v[182:185], v153 offset:3072
	s_add_u32 s6, s76, 0x20000
	s_addc_u32 s7, s77, 0
	s_mov_b32 m0, s79
	v_lshl_add_u64 v[224:225], s[6:7], 0, v[130:131]
	ds_read_b128 v[186:189], v152 offset:32768
	ds_read_b128 v[190:193], v152 offset:33792
	ds_read_b128 v[194:197], v152 offset:34816
	ds_read_b128 v[198:201], v152 offset:35840
	ds_read_b128 v[202:205], v152 offset:36864
	ds_read_b128 v[206:209], v152 offset:37888
	ds_read_b128 v[210:213], v152 offset:38912
	ds_read_b128 v[214:217], v152 offset:39936
	global_load_lds_dwordx4 v[224:225], off
	v_lshl_add_u64 v[224:225], s[6:7], 0, v[134:135]
	s_mov_b32 m0, s80
	s_nop 0
	global_load_lds_dwordx4 v[224:225], off
	s_waitcnt lgkmcnt(0)
	s_barrier
	s_setprio 1
	s_waitcnt lgkmcnt(0)
	v_mfma_f32_16x16x32_bf16 v[126:129], v[154:157], v[186:189], v[126:129]
	v_mfma_f32_16x16x32_bf16 v[122:125], v[162:165], v[186:189], v[122:125]
	v_mfma_f32_16x16x32_bf16 v[110:113], v[154:157], v[194:197], v[110:113]
	v_mfma_f32_16x16x32_bf16 v[106:109], v[162:165], v[194:197], v[106:109]
	v_mfma_f32_16x16x32_bf16 v[94:97], v[154:157], v[202:205], v[94:97]
	v_mfma_f32_16x16x32_bf16 v[90:93], v[162:165], v[202:205], v[90:93]
	v_mfma_f32_16x16x32_bf16 v[78:81], v[154:157], v[210:213], v[78:81]
	v_mfma_f32_16x16x32_bf16 v[74:77], v[162:165], v[210:213], v[74:77]
	v_mfma_f32_16x16x32_bf16 v[126:129], v[158:161], v[190:193], v[126:129]
	v_mfma_f32_16x16x32_bf16 v[122:125], v[166:169], v[190:193], v[122:125]
	v_mfma_f32_16x16x32_bf16 v[110:113], v[158:161], v[198:201], v[110:113]
	v_mfma_f32_16x16x32_bf16 v[106:109], v[166:169], v[198:201], v[106:109]
	v_mfma_f32_16x16x32_bf16 v[94:97], v[158:161], v[206:209], v[94:97]
	v_mfma_f32_16x16x32_bf16 v[90:93], v[166:169], v[206:209], v[90:93]
	v_mfma_f32_16x16x32_bf16 v[78:81], v[158:161], v[214:217], v[78:81]
	v_mfma_f32_16x16x32_bf16 v[74:77], v[166:169], v[214:217], v[74:77]
	s_setprio 0
	s_setprio 1
	v_mfma_f32_16x16x32_bf16 v[118:121], v[170:173], v[186:189], v[118:121]
	v_mfma_f32_16x16x32_bf16 v[114:117], v[178:181], v[186:189], v[114:117]
	v_mfma_f32_16x16x32_bf16 v[102:105], v[170:173], v[194:197], v[102:105]
	v_mfma_f32_16x16x32_bf16 v[98:101], v[178:181], v[194:197], v[98:101]
	v_mfma_f32_16x16x32_bf16 v[86:89], v[170:173], v[202:205], v[86:89]
	v_mfma_f32_16x16x32_bf16 v[82:85], v[178:181], v[202:205], v[82:85]
	v_mfma_f32_16x16x32_bf16 v[70:73], v[170:173], v[210:213], v[70:73]
	v_mfma_f32_16x16x32_bf16 v[66:69], v[178:181], v[210:213], v[66:69]
	v_mfma_f32_16x16x32_bf16 v[118:121], v[174:177], v[190:193], v[118:121]
	v_mfma_f32_16x16x32_bf16 v[114:117], v[182:185], v[190:193], v[114:117]
	v_mfma_f32_16x16x32_bf16 v[102:105], v[174:177], v[198:201], v[102:105]
	v_mfma_f32_16x16x32_bf16 v[98:101], v[182:185], v[198:201], v[98:101]
	v_mfma_f32_16x16x32_bf16 v[86:89], v[174:177], v[206:209], v[86:89]
	v_mfma_f32_16x16x32_bf16 v[82:85], v[182:185], v[206:209], v[82:85]
	v_mfma_f32_16x16x32_bf16 v[70:73], v[174:177], v[214:217], v[70:73]
	v_mfma_f32_16x16x32_bf16 v[66:69], v[182:185], v[214:217], v[66:69]
	s_setprio 0
	s_waitcnt vmcnt(8)
	s_barrier
	s_add_i32 s6, s95, s31
	v_lshl_add_u64 v[146:147], v[146:147], 0, s[20:21]
	s_mov_b32 m0, s6
	ds_read_b128 v[186:189], v152 offset:49152
	ds_read_b128 v[190:193], v152 offset:50176
	ds_read_b128 v[194:197], v152 offset:51200
	ds_read_b128 v[198:201], v152 offset:52224
	ds_read_b128 v[202:205], v152 offset:53248
	ds_read_b128 v[206:209], v152 offset:54272
	ds_read_b128 v[210:213], v152 offset:55296
	ds_read_b128 v[214:217], v152 offset:56320
	global_load_lds_dwordx4 v[146:147], off
	s_add_i32 m0, s6, 0x2000
	s_add_u32 s6, s74, 0x20080
	v_lshl_add_u64 v[146:147], v[218:219], 0, s[20:21]
	s_addc_u32 s7, s75, 0
	s_add_i32 s74, s96, s31
	global_load_lds_dwordx4 v[146:147], off
	v_lshl_add_u64 v[146:147], s[6:7], 0, v[132:133]
	s_mov_b32 m0, s74
	s_nop 0
	global_load_lds_dwordx4 v[146:147], off
	v_lshl_add_u64 v[146:147], s[6:7], 0, v[136:137]
	s_add_i32 m0, s74, 0x2000
	s_nop 0
	global_load_lds_dwordx4 v[146:147], off
	v_lshl_add_u64 v[146:147], v[220:221], 0, s[20:21]
	s_mov_b32 m0, s84
	s_nop 0
	global_load_lds_dwordx4 v[146:147], off
	v_lshl_add_u64 v[146:147], v[222:223], 0, s[20:21]
	s_mov_b32 m0, s85
	s_nop 0
	global_load_lds_dwordx4 v[146:147], off
	s_waitcnt lgkmcnt(0)
	s_barrier
	s_setprio 1
	s_waitcnt lgkmcnt(0)
	v_mfma_f32_16x16x32_bf16 v[62:65], v[154:157], v[186:189], v[62:65]
	v_mfma_f32_16x16x32_bf16 v[58:61], v[162:165], v[186:189], v[58:61]
	v_mfma_f32_16x16x32_bf16 v[46:49], v[154:157], v[194:197], v[46:49]
	v_mfma_f32_16x16x32_bf16 v[42:45], v[162:165], v[194:197], v[42:45]
	v_mfma_f32_16x16x32_bf16 v[30:33], v[154:157], v[202:205], v[30:33]
	v_mfma_f32_16x16x32_bf16 v[26:29], v[162:165], v[202:205], v[26:29]
	v_mfma_f32_16x16x32_bf16 v[14:17], v[154:157], v[210:213], v[14:17]
	v_mfma_f32_16x16x32_bf16 v[10:13], v[162:165], v[210:213], v[10:13]
	v_mfma_f32_16x16x32_bf16 v[62:65], v[158:161], v[190:193], v[62:65]
	v_mfma_f32_16x16x32_bf16 v[58:61], v[166:169], v[190:193], v[58:61]
	v_mfma_f32_16x16x32_bf16 v[46:49], v[158:161], v[198:201], v[46:49]
	v_mfma_f32_16x16x32_bf16 v[42:45], v[166:169], v[198:201], v[42:45]
	v_mfma_f32_16x16x32_bf16 v[30:33], v[158:161], v[206:209], v[30:33]
	v_mfma_f32_16x16x32_bf16 v[26:29], v[166:169], v[206:209], v[26:29]
	v_mfma_f32_16x16x32_bf16 v[14:17], v[158:161], v[214:217], v[14:17]
	v_mfma_f32_16x16x32_bf16 v[10:13], v[166:169], v[214:217], v[10:13]
	s_setprio 0
	s_setprio 1
	v_mfma_f32_16x16x32_bf16 v[54:57], v[170:173], v[186:189], v[54:57]
	v_mfma_f32_16x16x32_bf16 v[50:53], v[178:181], v[186:189], v[50:53]
	v_mfma_f32_16x16x32_bf16 v[38:41], v[170:173], v[194:197], v[38:41]
	v_mfma_f32_16x16x32_bf16 v[34:37], v[178:181], v[194:197], v[34:37]
	v_mfma_f32_16x16x32_bf16 v[22:25], v[170:173], v[202:205], v[22:25]
	v_mfma_f32_16x16x32_bf16 v[18:21], v[178:181], v[202:205], v[18:21]
	v_mfma_f32_16x16x32_bf16 v[6:9], v[170:173], v[210:213], v[6:9]
	v_mfma_f32_16x16x32_bf16 v[2:5], v[178:181], v[210:213], v[2:5]
	v_mfma_f32_16x16x32_bf16 v[54:57], v[174:177], v[190:193], v[54:57]
	v_mfma_f32_16x16x32_bf16 v[50:53], v[182:185], v[190:193], v[50:53]
	v_mfma_f32_16x16x32_bf16 v[38:41], v[174:177], v[198:201], v[38:41]
	v_mfma_f32_16x16x32_bf16 v[34:37], v[182:185], v[198:201], v[34:37]
	v_mfma_f32_16x16x32_bf16 v[22:25], v[174:177], v[206:209], v[22:25]
	v_mfma_f32_16x16x32_bf16 v[18:21], v[182:185], v[206:209], v[18:21]
	v_mfma_f32_16x16x32_bf16 v[6:9], v[174:177], v[214:217], v[6:9]
	v_mfma_f32_16x16x32_bf16 v[2:5], v[182:185], v[214:217], v[2:5]
	s_setprio 0
	s_waitcnt vmcnt(8)
	s_barrier
	s_add_i32 s94, s94, 2
	s_add_u32 s72, s72, 0x100
	s_addc_u32 s73, s73, 0
	s_add_u32 s92, s92, 0x100
	s_addc_u32 s93, s93, 0
	s_cmp_gt_u32 s94, 5
	s_cbranch_scc0 .LBB0_584
	s_branch .Lrwp3b_exit

.Lrwp6_bdone:
	s_mov_b32 s98, 0
	s_waitcnt lgkmcnt(0)
	s_barrier
	s_setprio 1
	s_waitcnt lgkmcnt(0)
	v_mfma_f32_16x16x32_bf16 v[62:65], v[156:159], v[188:191], 0
	v_mfma_f32_16x16x32_bf16 v[58:61], v[164:167], v[188:191], 0
	v_mfma_f32_16x16x32_bf16 v[46:49], v[156:159], v[196:199], 0
	v_mfma_f32_16x16x32_bf16 v[42:45], v[164:167], v[196:199], 0
	v_mfma_f32_16x16x32_bf16 v[30:33], v[156:159], v[204:207], 0
	v_mfma_f32_16x16x32_bf16 v[26:29], v[164:167], v[204:207], 0
	v_mfma_f32_16x16x32_bf16 v[14:17], v[156:159], v[212:215], 0
	v_mfma_f32_16x16x32_bf16 v[10:13], v[164:167], v[212:215], 0
	v_mfma_f32_16x16x32_bf16 v[62:65], v[160:163], v[192:195], v[62:65]
	v_mfma_f32_16x16x32_bf16 v[58:61], v[168:171], v[192:195], v[58:61]
	v_mfma_f32_16x16x32_bf16 v[46:49], v[160:163], v[200:203], v[46:49]
	v_mfma_f32_16x16x32_bf16 v[42:45], v[168:171], v[200:203], v[42:45]
	v_mfma_f32_16x16x32_bf16 v[30:33], v[160:163], v[208:211], v[30:33]
	v_mfma_f32_16x16x32_bf16 v[26:29], v[168:171], v[208:211], v[26:29]
	v_mfma_f32_16x16x32_bf16 v[14:17], v[160:163], v[216:219], v[14:17]
	v_mfma_f32_16x16x32_bf16 v[10:13], v[168:171], v[216:219], v[10:13]
	s_setprio 0
	s_setprio 1
	v_mfma_f32_16x16x32_bf16 v[54:57], v[172:175], v[188:191], 0
	v_mfma_f32_16x16x32_bf16 v[50:53], v[180:183], v[188:191], 0
	v_mfma_f32_16x16x32_bf16 v[38:41], v[172:175], v[196:199], 0
	v_mfma_f32_16x16x32_bf16 v[34:37], v[180:183], v[196:199], 0
	v_mfma_f32_16x16x32_bf16 v[22:25], v[172:175], v[204:207], 0
	v_mfma_f32_16x16x32_bf16 v[18:21], v[180:183], v[204:207], 0
	v_mfma_f32_16x16x32_bf16 v[6:9], v[172:175], v[212:215], 0
	v_mfma_f32_16x16x32_bf16 v[2:5], v[180:183], v[212:215], 0
	v_mfma_f32_16x16x32_bf16 v[54:57], v[176:179], v[192:195], v[54:57]
	v_mfma_f32_16x16x32_bf16 v[50:53], v[184:187], v[192:195], v[50:53]
	v_mfma_f32_16x16x32_bf16 v[38:41], v[176:179], v[200:203], v[38:41]
	v_mfma_f32_16x16x32_bf16 v[34:37], v[184:187], v[200:203], v[34:37]
	v_mfma_f32_16x16x32_bf16 v[22:25], v[176:179], v[208:211], v[22:25]
	v_mfma_f32_16x16x32_bf16 v[18:21], v[184:187], v[208:211], v[18:21]
	v_mfma_f32_16x16x32_bf16 v[6:9], v[176:179], v[216:219], v[6:9]
	v_mfma_f32_16x16x32_bf16 v[2:5], v[184:187], v[216:219], v[2:5]
	s_setprio 0
	s_barrier
	s_add_i32 s83, 0, 0x18000
	v_add_u32_e32 v138, s83, v151
	s_add_i32 s84, 0, 0x1c000
	ds_read_b128 v[156:159], v138
	ds_read_b128 v[160:163], v138 offset:1024
	ds_read_b128 v[164:167], v138 offset:2048
	ds_read_b128 v[168:171], v138 offset:3072
	v_add_u32_e32 v138, s84, v151
	ds_read_b128 v[172:175], v138
	ds_read_b128 v[176:179], v138 offset:1024
	ds_read_b128 v[180:183], v138 offset:2048
	ds_read_b128 v[184:187], v138 offset:3072
	s_add_u32 s6, s52, 0x40000
	s_addc_u32 s7, s53, 0
	s_mov_b32 m0, s56
	v_lshl_add_u64 v[226:227], s[6:7], 0, v[130:131]
	ds_read_b128 v[188:191], v154 offset:32768
	ds_read_b128 v[192:195], v154 offset:33792
	ds_read_b128 v[196:199], v154 offset:34816
	ds_read_b128 v[200:203], v154 offset:35840
	ds_read_b128 v[204:207], v154 offset:36864
	ds_read_b128 v[208:211], v154 offset:37888
	ds_read_b128 v[212:215], v154 offset:38912
	ds_read_b128 v[216:219], v154 offset:39936
	global_load_lds_dwordx4 v[226:227], off
	v_lshl_add_u64 v[226:227], s[6:7], 0, v[134:135]
	s_mov_b32 m0, s57
	s_nop 0
	global_load_lds_dwordx4 v[226:227], off
	s_waitcnt lgkmcnt(0)
	s_barrier
	s_setprio 1
	s_waitcnt lgkmcnt(0)
	v_mfma_f32_16x16x32_bf16 v[126:129], v[156:159], v[188:191], v[126:129]
	v_mfma_f32_16x16x32_bf16 v[122:125], v[164:167], v[188:191], v[122:125]
	v_mfma_f32_16x16x32_bf16 v[110:113], v[156:159], v[196:199], v[110:113]
	v_mfma_f32_16x16x32_bf16 v[106:109], v[164:167], v[196:199], v[106:109]
	v_mfma_f32_16x16x32_bf16 v[94:97], v[156:159], v[204:207], v[94:97]
	v_mfma_f32_16x16x32_bf16 v[90:93], v[164:167], v[204:207], v[90:93]
	v_mfma_f32_16x16x32_bf16 v[78:81], v[156:159], v[212:215], v[78:81]
	v_mfma_f32_16x16x32_bf16 v[74:77], v[164:167], v[212:215], v[74:77]
	v_mfma_f32_16x16x32_bf16 v[126:129], v[160:163], v[192:195], v[126:129]
	v_mfma_f32_16x16x32_bf16 v[122:125], v[168:171], v[192:195], v[122:125]
	v_mfma_f32_16x16x32_bf16 v[110:113], v[160:163], v[200:203], v[110:113]
	v_mfma_f32_16x16x32_bf16 v[106:109], v[168:171], v[200:203], v[106:109]
	v_mfma_f32_16x16x32_bf16 v[94:97], v[160:163], v[208:211], v[94:97]
	v_mfma_f32_16x16x32_bf16 v[90:93], v[168:171], v[208:211], v[90:93]
	v_mfma_f32_16x16x32_bf16 v[78:81], v[160:163], v[216:219], v[78:81]
	v_mfma_f32_16x16x32_bf16 v[74:77], v[168:171], v[216:219], v[74:77]
	s_setprio 0
	s_setprio 1
	v_mfma_f32_16x16x32_bf16 v[118:121], v[172:175], v[188:191], v[118:121]
	v_mfma_f32_16x16x32_bf16 v[114:117], v[180:183], v[188:191], v[114:117]
	v_mfma_f32_16x16x32_bf16 v[102:105], v[172:175], v[196:199], v[102:105]
	v_mfma_f32_16x16x32_bf16 v[98:101], v[180:183], v[196:199], v[98:101]
	v_mfma_f32_16x16x32_bf16 v[86:89], v[172:175], v[204:207], v[86:89]
	v_mfma_f32_16x16x32_bf16 v[82:85], v[180:183], v[204:207], v[82:85]
	v_mfma_f32_16x16x32_bf16 v[70:73], v[172:175], v[212:215], v[70:73]
	v_mfma_f32_16x16x32_bf16 v[66:69], v[180:183], v[212:215], v[66:69]
	v_mfma_f32_16x16x32_bf16 v[118:121], v[176:179], v[192:195], v[118:121]
	v_mfma_f32_16x16x32_bf16 v[114:117], v[184:187], v[192:195], v[114:117]
	v_mfma_f32_16x16x32_bf16 v[102:105], v[176:179], v[200:203], v[102:105]
	v_mfma_f32_16x16x32_bf16 v[98:101], v[184:187], v[200:203], v[98:101]
	v_mfma_f32_16x16x32_bf16 v[86:89], v[176:179], v[208:211], v[86:89]
	v_mfma_f32_16x16x32_bf16 v[82:85], v[184:187], v[208:211], v[82:85]
	v_mfma_f32_16x16x32_bf16 v[70:73], v[176:179], v[216:219], v[70:73]
	v_mfma_f32_16x16x32_bf16 v[66:69], v[184:187], v[216:219], v[66:69]
	s_setprio 0
	s_waitcnt vmcnt(8)
	s_barrier
	s_add_i32 s6, s83, s31
	v_lshl_add_u64 v[148:149], v[148:149], 0, s[16:17]
	s_mov_b32 m0, s6
	ds_read_b128 v[188:191], v154 offset:49152
	ds_read_b128 v[192:195], v154 offset:50176
	ds_read_b128 v[196:199], v154 offset:51200
	ds_read_b128 v[200:203], v154 offset:52224
	ds_read_b128 v[204:207], v154 offset:53248
	ds_read_b128 v[208:211], v154 offset:54272
	ds_read_b128 v[212:215], v154 offset:55296
	ds_read_b128 v[216:219], v154 offset:56320
	global_load_lds_dwordx4 v[148:149], off
	s_add_i32 m0, s6, 0x2000
	s_add_u32 s6, s50, 0x40080
	v_lshl_add_u64 v[148:149], v[220:221], 0, s[16:17]
	s_addc_u32 s7, s51, 0
	s_add_i32 s50, s84, s31
	global_load_lds_dwordx4 v[148:149], off
	v_lshl_add_u64 v[148:149], s[6:7], 0, v[132:133]
	s_mov_b32 m0, s50
	s_nop 0
	global_load_lds_dwordx4 v[148:149], off
	v_lshl_add_u64 v[148:149], s[6:7], 0, v[136:137]
	s_add_i32 m0, s50, 0x2000
	s_nop 0
	global_load_lds_dwordx4 v[148:149], off
	v_lshl_add_u64 v[148:149], v[222:223], 0, s[16:17]
	s_mov_b32 m0, s60
	s_nop 0
	global_load_lds_dwordx4 v[148:149], off
	v_lshl_add_u64 v[148:149], v[224:225], 0, s[16:17]
	s_mov_b32 m0, s61
	s_nop 0
	global_load_lds_dwordx4 v[148:149], off
	s_waitcnt lgkmcnt(0)
	s_barrier
	s_setprio 1
	s_waitcnt lgkmcnt(0)
	v_mfma_f32_16x16x32_bf16 v[62:65], v[156:159], v[188:191], v[62:65]
	v_mfma_f32_16x16x32_bf16 v[58:61], v[164:167], v[188:191], v[58:61]
	v_mfma_f32_16x16x32_bf16 v[46:49], v[156:159], v[196:199], v[46:49]
	v_mfma_f32_16x16x32_bf16 v[42:45], v[164:167], v[196:199], v[42:45]
	v_mfma_f32_16x16x32_bf16 v[30:33], v[156:159], v[204:207], v[30:33]
	v_mfma_f32_16x16x32_bf16 v[26:29], v[164:167], v[204:207], v[26:29]
	v_mfma_f32_16x16x32_bf16 v[14:17], v[156:159], v[212:215], v[14:17]
	v_mfma_f32_16x16x32_bf16 v[10:13], v[164:167], v[212:215], v[10:13]
	v_mfma_f32_16x16x32_bf16 v[62:65], v[160:163], v[192:195], v[62:65]
	v_mfma_f32_16x16x32_bf16 v[58:61], v[168:171], v[192:195], v[58:61]
	v_mfma_f32_16x16x32_bf16 v[46:49], v[160:163], v[200:203], v[46:49]
	v_mfma_f32_16x16x32_bf16 v[42:45], v[168:171], v[200:203], v[42:45]
	v_mfma_f32_16x16x32_bf16 v[30:33], v[160:163], v[208:211], v[30:33]
	v_mfma_f32_16x16x32_bf16 v[26:29], v[168:171], v[208:211], v[26:29]
	v_mfma_f32_16x16x32_bf16 v[14:17], v[160:163], v[216:219], v[14:17]
	v_mfma_f32_16x16x32_bf16 v[10:13], v[168:171], v[216:219], v[10:13]
	s_setprio 0
	s_setprio 1
	v_mfma_f32_16x16x32_bf16 v[54:57], v[172:175], v[188:191], v[54:57]
	v_mfma_f32_16x16x32_bf16 v[50:53], v[180:183], v[188:191], v[50:53]
	v_mfma_f32_16x16x32_bf16 v[38:41], v[172:175], v[196:199], v[38:41]
	v_mfma_f32_16x16x32_bf16 v[34:37], v[180:183], v[196:199], v[34:37]
	v_mfma_f32_16x16x32_bf16 v[22:25], v[172:175], v[204:207], v[22:25]
	v_mfma_f32_16x16x32_bf16 v[18:21], v[180:183], v[204:207], v[18:21]
	v_mfma_f32_16x16x32_bf16 v[6:9], v[172:175], v[212:215], v[6:9]
	v_mfma_f32_16x16x32_bf16 v[2:5], v[180:183], v[212:215], v[2:5]
	v_mfma_f32_16x16x32_bf16 v[54:57], v[176:179], v[192:195], v[54:57]
	v_mfma_f32_16x16x32_bf16 v[50:53], v[184:187], v[192:195], v[50:53]
	v_mfma_f32_16x16x32_bf16 v[38:41], v[176:179], v[200:203], v[38:41]
	v_mfma_f32_16x16x32_bf16 v[34:37], v[184:187], v[200:203], v[34:37]
	v_mfma_f32_16x16x32_bf16 v[22:25], v[176:179], v[208:211], v[22:25]
	v_mfma_f32_16x16x32_bf16 v[18:21], v[184:187], v[208:211], v[18:21]
	v_mfma_f32_16x16x32_bf16 v[6:9], v[176:179], v[216:219], v[6:9]
	v_mfma_f32_16x16x32_bf16 v[2:5], v[184:187], v[216:219], v[2:5]
	s_setprio 0
	s_waitcnt vmcnt(8)
	s_barrier
	s_add_i32 s82, s82, 2
	s_add_u32 s48, s48, 0x100
	s_addc_u32 s49, s49, 0
	s_add_u32 s80, s80, 0x100
	s_addc_u32 s81, s81, 0
	s_cmp_gt_u32 s82, 13
	s_cbranch_scc0 .LBB0_780
	s_branch .Lrwp6_exit
